# NSA selected+window loops: next step's tile-list ds_read issued mid-step right after the current entries are consumed (latency no longer exposed before the step barrier); fused-path temps moved off v2
# baseline (speedup 1.0000x reference)
; #define CO_STEP2(list, n, i) do { \
;     if ((n) - 1 - (i) >= 1) asm volatile("s_waitcnt vmcnt(2)" ::: "memory"); else asm volatile("s_waitcnt vmcnt(0)" ::: "memory"); \
;     asm volatile("s_waitcnt lgkmcnt(0)" ::: "memory"); __builtin_amdgcn_s_barrier(); asm volatile("" ::: "memory"); \
;     if ((i) + 2 < (n)) co_issue(P, ring, ((i) + 2) & 3, (list)[(i) + 2], b, g, wave, lane); } while (0)
; #define CO_PIPE(MODE, REL, KB, RS) do { const bool rel_ = (REL); LAS unsigned char* sp_ = ring + (i & 3) * 16384; f32x16 Sn_; \
;     if (rel_) Sn_ = co_qk1(sp_, qf, ka); \
;     if (pend) co_finish<MODE>(Sp, pst, pkb, st, tq, prs, vb, hh); \
;     pend = rel_; if (rel_) { Sp = Sn_; pst = sp_; pkb = (KB); prs = (RS); } } while (0)
; DI void attn_reset(AttnState& st) {
;     st.m = -1e30f; st.l = 0.f;
; #pragma unroll
;     for (int dt = 0; dt < 4; ++dt)
; #pragma unroll
;         for (int i = 0; i < 16; ++i) st.acc[dt][i] = 0.f;
; }
; DI void nsa_block_item(const Params& P, unsigned char* smem_g, int b, int g, int tb, int tid_in) {
;     ...
;     const int curw = t0 >> 6; const unsigned validw = (curw >= 31) ? 0xffffffffu : ((2u << curw) - 1u);
;     const unsigned Uw = (unsigned)__builtin_amdgcn_readfirstlane((int)((selm[0] | selm[1] | selm[2] | selm[3]) & validw));
;     if (lane == 0) uw[wave] = Uw;
;     attn_reset(st);
;     for (; i < n1; ++i) { CO_STEP2(list1, n1, i); const int kb_ = lo + 32 * (i - 2 * nA); CO_PIPE(2, kb_ + 31 >= t0 - 511 && kb_ <= t0 + 3, kb_, true); }
.LBB0_503:
	s_or_b64 exec, exec, s[8:9]
	s_lshl_b32 s0, 2, s41
	s_add_i32 s0, s0, -1
	s_cmp_lt_i32 s41, 31
	s_cselect_b32 s2, s0, -1
	s_or_b64 s[0:1], vcc, s[4:5]
	s_or_b32 s0, s4, s1
	s_or_b32 s0, s0, vcc_lo
	s_and_b32 s70, s2, s0
	v_cmp_eq_u32_e32 vcc, 0, v155
	s_and_saveexec_b64 s[2:3], vcc
	s_add_i32 s0, s61, 0
	s_add_i32 s0, s0, 0x25400
	v_mov_b32_e32 v0, s0
	v_mov_b32_e32 v2, s70
	ds_write_b32 v0, v2
	s_or_b64 exec, exec, s[2:3]
	s_sub_i32 s79, 0, s64
	s_cmp_gt_i32 s40, s33
	v_sub_u32_e32 v145, v175, v177
	s_cbranch_scc1 .LBB0_525
	s_add_i32 s71, s59, 0xfffffe01
	s_or_b32 s72, s59, 3
	s_lshl_b32 s0, s67, 1
	s_add_u32 s0, s30, s0
	s_addc_u32 s1, s31, 0
	s_lshl_b32 s2, s22, 1
	s_add_u32 s4, s21, s2
	s_addc_u32 s5, s23, 0
	s_lshl_b32 s2, s66, 1
	s_add_u32 s73, s0, s2
	s_addc_u32 s74, s1, 0
	s_lshl_b32 s0, s40, 5
	s_add_i32 s0, s0, s69
	s_lshl_b32 s1, s68, 6
	s_sub_i32 s68, s0, s1
	s_lshl_b32 s0, s40, 2
	v_mov_b32_e32 v14, v1
	v_mov_b32_e32 v15, v1
	s_add_i32 s0, s0, 0
	v_mov_b32_e32 v0, v1
	v_mov_b32_e32 v2, v1
	v_mov_b32_e32 v3, v1
	v_mov_b32_e32 v4, v1
	v_mov_b32_e32 v5, v1
	v_mov_b32_e32 v6, v1
	v_mov_b32_e32 v7, v1
	v_mov_b32_e32 v8, v1
	v_mov_b32_e32 v9, v1
	v_mov_b32_e32 v10, v1
	v_mov_b32_e32 v11, v1
	v_mov_b32_e32 v12, v1
	v_mov_b32_e32 v13, v1
	v_mov_b64_e32 v[94:95], v[14:15]
	v_mov_b64_e32 v[78:79], v[14:15]
	v_mov_b64_e32 v[62:63], v[14:15]
	v_mov_b64_e32 v[46:47], v[14:15]
	s_add_i32 s75, s65, 0
	s_lshl_b32 s76, s40, 14
	s_add_i32 s69, s0, 0x25008
	s_add_i32 s77, s40, 2
	v_mov_b32_e32 v175, 0
	v_mov_b32_e32 v177, 0xf149f2ca
	s_mov_b64 s[36:37], 0
	v_mov_b64_e32 v[92:93], v[12:13]
	v_mov_b64_e32 v[90:91], v[10:11]
	v_mov_b64_e32 v[88:89], v[8:9]
	v_mov_b64_e32 v[86:87], v[6:7]
	v_mov_b64_e32 v[84:85], v[4:5]
	v_mov_b64_e32 v[82:83], v[2:3]
	v_mov_b64_e32 v[80:81], v[0:1]
	v_mov_b64_e32 v[76:77], v[12:13]
	v_mov_b64_e32 v[74:75], v[10:11]
	v_mov_b64_e32 v[72:73], v[8:9]
	v_mov_b64_e32 v[70:71], v[6:7]
	v_mov_b64_e32 v[68:69], v[4:5]
	v_mov_b64_e32 v[66:67], v[2:3]
	v_mov_b64_e32 v[64:65], v[0:1]
	v_mov_b64_e32 v[60:61], v[12:13]
	v_mov_b64_e32 v[58:59], v[10:11]
	v_mov_b64_e32 v[56:57], v[8:9]
	v_mov_b64_e32 v[54:55], v[6:7]
	v_mov_b64_e32 v[52:53], v[4:5]
	v_mov_b64_e32 v[50:51], v[2:3]
	v_mov_b64_e32 v[48:49], v[0:1]
	v_mov_b64_e32 v[44:45], v[12:13]
	v_mov_b64_e32 v[42:43], v[10:11]
	v_mov_b64_e32 v[40:41], v[8:9]
	v_mov_b64_e32 v[38:39], v[6:7]
	v_mov_b64_e32 v[36:37], v[4:5]
	v_mov_b64_e32 v[34:35], v[2:3]
	v_mov_b64_e32 v[32:33], v[0:1]
	v_mov_b32_e32 v239, s69
	ds_read_b32 v238, v239
	s_add_i32 s78, s77, -2
	s_cmp_le_i32 s33, s78
	s_mov_b64 s[2:3], -1
	s_cbranch_scc0 .LBB0_508

.LBB0_508:
	s_andn2_b64 vcc, exec, s[2:3]
	s_cbranch_vccnz .LBB0_510
	s_waitcnt vmcnt(2)
.LBB0_510:
	s_waitcnt lgkmcnt(0)
	s_barrier
	s_cmp_gt_i32 s77, s33
	s_cbranch_scc1 .LBB0_515
	v_cmp_gt_u32_e32 vcc, s46, v238
	v_readfirstlane_b32 s81, v238
	s_cbranch_vccnz .LBB0_513
	s_cmp_lt_u32 s81, 0x30000
	s_cselect_b32 s0, 0x4000, s51
	s_cselect_b32 s16, s50, 0x3c800000
	s_add_u32 s2, s73, s0
	s_addc_u32 s3, s74, 0
	s_movk_i32 s82, 0x7600
	s_movk_i32 s80, 0x1000
	s_mov_b64 s[8:9], s[16:17]
	s_mov_b64 s[40:41], s[20:21]
	s_branch .LBB0_514

; #define CO_STEP2(list, n, i) do { \
;     if ((n) - 1 - (i) >= 1) asm volatile("s_waitcnt vmcnt(2)" ::: "memory"); else asm volatile("s_waitcnt vmcnt(0)" ::: "memory"); \
;     asm volatile("s_waitcnt lgkmcnt(0)" ::: "memory"); __builtin_amdgcn_s_barrier(); asm volatile("" ::: "memory"); \
;     if ((i) + 2 < (n)) co_issue(P, ring, ((i) + 2) & 3, (list)[(i) + 2], b, g, wave, lane); } while (0)
; #define CO_PIPE(MODE, REL, KB, RS) do { const bool rel_ = (REL); LAS unsigned char* sp_ = ring + (i & 3) * 16384; f32x16 Sn_; \
;     if (rel_) Sn_ = co_qk1(sp_, qf, ka); \
;     if (pend) co_finish<MODE>(Sp, pst, pkb, st, tq, prs, vb, hh); \
;     pend = rel_; if (rel_) { Sp = Sn_; pst = sp_; pkb = (KB); prs = (RS); } } while (0)
; DI void nsa_block_item(const Params& P, unsigned char* smem_g, int b, int g, int tb, int tid_in) {
;     ...
;     for (; i < n1; ++i) { CO_STEP2(list1, n1, i); const int kb_ = lo + 32 * (i - 2 * nA); CO_PIPE(2, kb_ + 31 >= t0 - 511 && kb_ <= t0 + 3, kb_, true); }
.LBB0_515:
	s_add_i32 s98, s69, 4
	v_mov_b32_e32 v239, s98
	ds_read_b32 v238, v239
	s_add_i32 s0, s68, 31
	s_cmp_ge_i32 s0, s71
	s_cselect_b64 s[0:1], -1, 0
	s_cmp_le_i32 s68, s72
	s_cselect_b64 s[2:3], -1, 0
	s_and_b64 s[8:9], s[0:1], s[2:3]
	s_and_b32 s16, s76, 0xc000
	v_cndmask_b32_e64 v0, 0, 1, s[8:9]
	v_cmp_ne_u32_e64 s[2:3], 1, v0
	s_andn2_b64 vcc, exec, s[8:9]
	s_add_i32 s16, s16, 0
	s_cbranch_vccnz .LBB0_517
	s_andn2_b64 vcc, exec, s[36:37]
	s_cbranch_vccnz .Lfast_win_orig
	s_add_i32 s88, s72, s79
	s_sub_i32 s88, s88, 34
	s_cmp_lt_u32 s88, 0x1de
	s_cbranch_scc1 .Lfast_win
	s_branch .Lfs_win

; #define CO_STEP2(list, n, i) do { \
;     if ((n) - 1 - (i) >= 1) asm volatile("s_waitcnt vmcnt(2)" ::: "memory"); else asm volatile("s_waitcnt vmcnt(0)" ::: "memory"); \
;     asm volatile("s_waitcnt lgkmcnt(0)" ::: "memory"); __builtin_amdgcn_s_barrier(); asm volatile("" ::: "memory"); \
;     if ((i) + 2 < (n)) co_issue(P, ring, ((i) + 2) & 3, (list)[(i) + 2], b, g, wave, lane); } while (0)
; #define CO_PIPE(MODE, REL, KB, RS) do { const bool rel_ = (REL); LAS unsigned char* sp_ = ring + (i & 3) * 16384; f32x16 Sn_; \
;     if (rel_) Sn_ = co_qk1(sp_, qf, ka); \
;     if (pend) co_finish<MODE>(Sp, pst, pkb, st, tq, prs, vb, hh); \
;     pend = rel_; if (rel_) { Sp = Sn_; pst = sp_; pkb = (KB); prs = (RS); } } while (0)
; DI void nsa_block_item(const Params& P, unsigned char* smem_g, int b, int g, int tb, int tid_in) {
;     ...
;     for (i = 0; i < n2; ++i) {
;         CO_STEP2(list2, n2, i); const int kb_ = (int)(list2[i] & 0xffffu); const int j = kb_ >> 6;
;         CO_PIPE(1, ((Uw >> j) & 1u) && kb_ <= t0 + 3, kb_, (bool)((mysel >> j) & 1u));
.LBB0_546:
	v_readfirstlane_b32 s0, v237
	s_add_i32 s98, s71, 4
	v_mov_b32_e32 v239, s98
	ds_read_b32 v238, v239 offset:8
	ds_read_b32 v237, v239
	s_and_b32 s16, s0, 0xffff
	s_bfe_u32 s0, s0, 0xa0006
	s_lshl_b32 s41, 1, s0
	s_and_b32 s0, s41, s70
	s_cmp_lg_u32 s0, 0
	s_cselect_b64 s[0:1], -1, 0
	s_cmp_le_i32 s16, s25
	s_cselect_b64 s[2:3], -1, 0
	s_and_b64 s[8:9], s[0:1], s[2:3]
	s_and_b32 s40, s72, 0xc000
	v_cndmask_b32_e64 v0, 0, 1, s[8:9]
	v_cmp_ne_u32_e64 s[2:3], 1, v0
	s_andn2_b64 vcc, exec, s[8:9]
	s_add_i32 s40, s40, 0
	s_cbranch_vccnz .LBB0_548
	s_andn2_b64 vcc, exec, s[36:37]
	s_cbranch_vccnz .Lfast_sel_orig
	s_add_i32 s88, s59, s74
	s_cmp_ge_i32 s88, 31
	s_cbranch_scc1 .Lfast_sel
	s_branch .Lfs_sel

; #define LAS __attribute__((address_space(3)))
; DI float xh_max(float x) { const unsigned u = __float_as_uint(x); const auto r = __builtin_amdgcn_permlane32_swap(u, u, false, false); return fmaxf(__uint_as_float(r[0]), __uint_as_float(r[1])); }
; DI float xh_sum(float x) { const unsigned u = __float_as_uint(x); const auto r = __builtin_amdgcn_permlane32_swap(u, u, false, false); return __uint_as_float(r[0]) + __uint_as_float(r[1]); }
; #define MFMA32(a, b, c) __builtin_amdgcn_mfma_f32_32x32x16_bf16((a), (b), (c), 0, 0, 0)
; DI f32x16 co_qk1(LAS unsigned char* st, const bf16x8 (&qf)[8], int ka_in) {
;     const int ka = ka_in;
;     f32x16 S;
; #pragma unroll
;     for (int i = 0; i < 16; ++i) S[i] = 0.f;
;     __builtin_amdgcn_s_setprio(1);
; #pragma unroll
;     for (int ks = 0; ks < 8; ++ks) { const bf16x8 a = *(const LAS bf16x8*)(st + (ka ^ (32 * ks))); S = MFMA32(a, qf[ks], S); }
;     __builtin_amdgcn_s_setprio(0);
;     return S;
; }
; template <int MODE>
; DI void co_finish(f32x16 S, LAS unsigned char* st, int key_base, AttnState& as, int tq, bool rowsel, int vb_in, int hh) {
;     const int vb = vb_in;
;     {
;         const int base = key_base + 4 * hh;
;         const int hi = (MODE == 0) ? (((tq - 31) >> 4) - base) : (tq - base);
;         const int lo = hi - 512;
; #pragma unroll
;         for (int i = 0; i < 16; ++i) { const int c = (i & 3) + 8 * (i >> 2); bool ok = (c <= hi); if (MODE == 2) ok = ok && (c > lo); if (MODE == 1) ok = ok && rowsel; S[i] = ok ? S[i] : -1e30f; }
;     }
;     float mx = S[0];
; #pragma unroll
;     for (int i = 1; i < 16; ++i) mx = fmaxf(mx, S[i]);
;     mx = xh_max(mx);
;     const float mxs = mx * SM_SCALE; const bool need = mxs > as.m + 8.f;
;     const float mnew = need ? mxs : as.m, muse = -fmaxf(mnew, -1e20f); float ps = 0.f;
; #pragma unroll
;     for (int i = 0; i < 16; ++i) { const float p = __builtin_amdgcn_exp2f(__builtin_fmaf(S[i], SM_SCALE, muse)); S[i] = p; ps += p; }
;     ps = xh_sum(ps);
.Lfs_sel:
	v_add_u32_e32 v248, s40, v162
	ds_read_b128 v[240:243], v248
	v_add_u32_e32 v248, s40, v164
	ds_read_b128 v[244:247], v248
	v_add_u32_e32 v0, s74, v145
	v_cmp_lt_i32_e32 vcc, -1, v0
	s_and_b64 vcc, s[26:27], vcc
	s_nop 0
	v_cndmask_b32_e32 v2, v153, v16, vcc
	v_cmp_lt_i32_e32 vcc, 0, v0
	s_and_b64 vcc, s[26:27], vcc
	v_max_f32_e32 v174, v2, v2
	v_cndmask_b32_e32 v3, v153, v17, vcc
	v_cmp_lt_i32_e32 vcc, 1, v0
	s_and_b64 vcc, s[26:27], vcc
	s_nop 0
	v_cndmask_b32_e32 v4, v153, v18, vcc
	s_waitcnt lgkmcnt(1)
	v_mfma_f32_32x32x16_bf16 v[96:111], v[240:243], v[112:115], 0
	v_add_u32_e32 v248, s40, v165
	ds_read_b128 v[240:243], v248
	v_cmp_lt_i32_e32 vcc, 2, v0
	s_and_b64 vcc, s[26:27], vcc
	s_nop 0
	v_cndmask_b32_e32 v5, v153, v19, vcc
	v_cmp_lt_i32_e32 vcc, 7, v0
	s_and_b64 vcc, s[26:27], vcc
	s_nop 0
	v_cndmask_b32_e32 v6, v153, v20, vcc
	v_cmp_lt_i32_e32 vcc, 8, v0
	s_and_b64 vcc, s[26:27], vcc
	s_nop 0
	v_cndmask_b32_e32 v7, v153, v21, vcc
	v_cmp_lt_i32_e32 vcc, 9, v0
	s_and_b64 vcc, s[26:27], vcc
	s_waitcnt lgkmcnt(1)
	v_mfma_f32_32x32x16_bf16 v[96:111], v[244:247], v[116:119], v[96:111]
	v_add_u32_e32 v248, s40, v166
	ds_read_b128 v[244:247], v248
	s_nop 0
	v_cndmask_b32_e32 v8, v153, v22, vcc
	v_cmp_lt_i32_e32 vcc, 10, v0
	s_and_b64 vcc, s[26:27], vcc
	s_nop 0
	v_cndmask_b32_e32 v9, v153, v23, vcc
	v_cmp_lt_i32_e32 vcc, 15, v0
	s_and_b64 vcc, s[26:27], vcc
	s_nop 0
	v_cndmask_b32_e32 v10, v153, v24, vcc
	v_cmp_lt_i32_e32 vcc, 16, v0
	s_and_b64 vcc, s[26:27], vcc
	s_nop 0
	v_cndmask_b32_e32 v11, v153, v25, vcc
	s_waitcnt lgkmcnt(1)
	v_mfma_f32_32x32x16_bf16 v[96:111], v[240:243], v[120:123], v[96:111]
	v_add_u32_e32 v248, s40, v167
	ds_read_b128 v[240:243], v248
	v_cmp_lt_i32_e32 vcc, 17, v0
	s_and_b64 vcc, s[26:27], vcc
	s_nop 0
	v_cndmask_b32_e32 v12, v153, v26, vcc
	v_cmp_lt_i32_e32 vcc, 18, v0
	s_and_b64 vcc, s[26:27], vcc
	s_nop 0
	v_cndmask_b32_e32 v13, v153, v27, vcc
	v_cmp_lt_i32_e32 vcc, 23, v0
	s_and_b64 vcc, s[26:27], vcc
	s_nop 0
	v_cndmask_b32_e32 v14, v153, v28, vcc
	v_cmp_lt_i32_e32 vcc, 24, v0
	s_waitcnt lgkmcnt(1)
	v_mfma_f32_32x32x16_bf16 v[96:111], v[244:247], v[124:127], v[96:111]
	v_add_u32_e32 v248, s40, v168
	ds_read_b128 v[244:247], v248
	s_and_b64 vcc, s[26:27], vcc
	s_nop 0
	v_cndmask_b32_e32 v15, v153, v29, vcc
	v_cmp_lt_i32_e32 vcc, 25, v0
	s_and_b64 vcc, s[26:27], vcc
	s_nop 0
	v_cndmask_b32_e32 v176, v153, v30, vcc
	v_cmp_lt_i32_e32 vcc, 26, v0
	v_max_f32_e32 v0, v3, v3
	v_max_f32_e32 v0, v174, v0
	v_max3_f32 v0, v0, v4, v5
	v_max3_f32 v0, v0, v6, v7
	v_max3_f32 v0, v0, v8, v9
	v_max3_f32 v0, v0, v10, v11
	s_waitcnt lgkmcnt(1)
	v_mfma_f32_32x32x16_bf16 v[96:111], v[240:243], v[128:131], v[96:111]
	v_add_u32_e32 v248, s40, v169
	ds_read_b128 v[240:243], v248
	s_and_b64 vcc, s[26:27], vcc
	v_max3_f32 v0, v0, v12, v13
	v_cndmask_b32_e32 v177, v153, v31, vcc
	v_max3_f32 v0, v0, v14, v15
	v_max3_f32 v0, v0, v176, v177
	v_mov_b32_e32 v174, v0
	s_nop 1
	v_permlane32_swap_b32_e32 v0, v174
	v_max_f32_e32 v174, v174, v174
	v_max_f32_e32 v0, v0, v0
	v_max_f32_e32 v0, v0, v174
	v_mul_f32_e32 v0, 0x3e0293ee, v0
	v_add_f32_e32 v174, 0x41000000, v175
	v_cmp_gt_f32_e32 vcc, v0, v174
	s_waitcnt lgkmcnt(1)
	v_mfma_f32_32x32x16_bf16 v[96:111], v[244:247], v[132:135], v[96:111]
	v_add_u32_e32 v248, s40, v170
	ds_read_b128 v[244:247], v248
	s_nop 1
	v_cndmask_b32_e32 v174, v175, v0, vcc
	v_max_f32_e32 v0, v174, v174
	v_max_f32_e32 v178, 0xe0ad78ec, v0
	v_fma_f32 v0, v2, s52, -v178
	v_exp_f32_e32 v0, v0
	v_fma_f32 v2, v3, s52, -v178
	v_exp_f32_e32 v2, v2
	v_fma_f32 v3, v4, s52, -v178
	v_exp_f32_e32 v3, v3
	v_fma_f32 v4, v5, s52, -v178
	v_exp_f32_e32 v4, v4
	v_add_f32_e32 v5, 0, v0
	s_waitcnt lgkmcnt(1)
	v_mfma_f32_32x32x16_bf16 v[96:111], v[240:243], v[136:139], v[96:111]
	v_add_f32_e32 v5, v2, v5
	v_add_f32_e32 v5, v3, v5
	v_add_f32_e32 v179, v4, v5
	v_fma_f32 v5, v6, s52, -v178
	v_exp_f32_e32 v5, v5
	v_fma_f32 v6, v7, s52, -v178
	v_exp_f32_e32 v6, v6
	v_fma_f32 v7, v8, s52, -v178
	v_exp_f32_e32 v7, v7
	v_fma_f32 v8, v9, s52, -v178
	v_exp_f32_e32 v8, v8
	v_add_f32_e32 v9, v5, v179
	v_add_f32_e32 v9, v6, v9
	v_add_f32_e32 v9, v7, v9
	s_waitcnt lgkmcnt(0)
	v_mfma_f32_32x32x16_bf16 v[96:111], v[244:247], v[140:143], v[96:111]
	v_add_f32_e32 v179, v8, v9
	v_fma_f32 v9, v10, s52, -v178
	v_exp_f32_e32 v9, v9
	v_fma_f32 v10, v11, s52, -v178
	v_exp_f32_e32 v10, v10
	v_fma_f32 v11, v12, s52, -v178
	v_exp_f32_e32 v11, v11
	v_fma_f32 v12, v13, s52, -v178
	v_exp_f32_e32 v12, v12
	v_add_f32_e32 v13, v9, v179
	v_add_f32_e32 v13, v10, v13
	v_add_f32_e32 v13, v11, v13
	v_add_f32_e32 v179, v12, v13
	v_fma_f32 v13, v14, s52, -v178
	v_exp_f32_e32 v13, v13
	v_fma_f32 v14, v15, s52, -v178
	v_exp_f32_e32 v14, v14
	v_fma_f32 v15, v176, s52, -v178
	v_exp_f32_e32 v15, v15
	v_fma_f32 v176, v177, s52, -v178
	v_exp_f32_e32 v176, v176
	v_add_f32_e32 v177, v13, v179
	v_add_f32_e32 v177, v14, v177
	v_add_f32_e32 v177, v15, v177
	v_add_f32_e32 v177, v176, v177
	v_mov_b32_e32 v178, v177
	s_nop 1
	v_permlane32_swap_b32_e32 v177, v178
	s_cbranch_vccz .Lfs_sel_551
; template <int MODE>
; DI void co_finish(f32x16 S, LAS unsigned char* st, int key_base, AttnState& as, int tq, bool rowsel, int vb_in, int hh) {
;     ...
;     if (__builtin_amdgcn_ballot_w64(need) != 0ull) {
;         const float alpha = __builtin_amdgcn_exp2f(as.m - mnew);
;         as.l *= alpha;
; #pragma unroll
;         for (int dt = 0; dt < 4; ++dt)
; #pragma unroll
;             for (int i = 0; i < 16; ++i) as.acc[dt][i] *= alpha;
;     }
	v_sub_f32_e32 v175, v175, v174
	v_exp_f32_e32 v180, v175
	s_nop 0
	v_mul_f32_e32 v163, v163, v180
	v_pk_mul_f32 v[94:95], v[94:95], v[180:181] op_sel_hi:[1,0]
	v_pk_mul_f32 v[92:93], v[92:93], v[180:181] op_sel_hi:[1,0]
	v_pk_mul_f32 v[90:91], v[90:91], v[180:181] op_sel_hi:[1,0]
	v_pk_mul_f32 v[88:89], v[88:89], v[180:181] op_sel_hi:[1,0]
	v_pk_mul_f32 v[86:87], v[86:87], v[180:181] op_sel_hi:[1,0]
	v_pk_mul_f32 v[84:85], v[84:85], v[180:181] op_sel_hi:[1,0]
	v_pk_mul_f32 v[82:83], v[82:83], v[180:181] op_sel_hi:[1,0]
	v_pk_mul_f32 v[80:81], v[80:81], v[180:181] op_sel_hi:[1,0]
	v_pk_mul_f32 v[78:79], v[78:79], v[180:181] op_sel_hi:[1,0]
	v_pk_mul_f32 v[76:77], v[76:77], v[180:181] op_sel_hi:[1,0]
	v_pk_mul_f32 v[74:75], v[74:75], v[180:181] op_sel_hi:[1,0]
	v_pk_mul_f32 v[72:73], v[72:73], v[180:181] op_sel_hi:[1,0]
	v_pk_mul_f32 v[70:71], v[70:71], v[180:181] op_sel_hi:[1,0]
	v_pk_mul_f32 v[68:69], v[68:69], v[180:181] op_sel_hi:[1,0]
	v_pk_mul_f32 v[66:67], v[66:67], v[180:181] op_sel_hi:[1,0]
	v_pk_mul_f32 v[64:65], v[64:65], v[180:181] op_sel_hi:[1,0]
	v_pk_mul_f32 v[62:63], v[62:63], v[180:181] op_sel_hi:[1,0]
	v_pk_mul_f32 v[60:61], v[60:61], v[180:181] op_sel_hi:[1,0]
	v_pk_mul_f32 v[58:59], v[58:59], v[180:181] op_sel_hi:[1,0]
	v_pk_mul_f32 v[56:57], v[56:57], v[180:181] op_sel_hi:[1,0]
	v_pk_mul_f32 v[54:55], v[54:55], v[180:181] op_sel_hi:[1,0]
	v_pk_mul_f32 v[52:53], v[52:53], v[180:181] op_sel_hi:[1,0]
	v_pk_mul_f32 v[50:51], v[50:51], v[180:181] op_sel_hi:[1,0]
	v_pk_mul_f32 v[48:49], v[48:49], v[180:181] op_sel_hi:[1,0]
	v_pk_mul_f32 v[46:47], v[46:47], v[180:181] op_sel_hi:[1,0]
	v_pk_mul_f32 v[44:45], v[44:45], v[180:181] op_sel_hi:[1,0]
	v_pk_mul_f32 v[42:43], v[42:43], v[180:181] op_sel_hi:[1,0]
	v_pk_mul_f32 v[40:41], v[40:41], v[180:181] op_sel_hi:[1,0]
	v_pk_mul_f32 v[38:39], v[38:39], v[180:181] op_sel_hi:[1,0]
	v_pk_mul_f32 v[36:37], v[36:37], v[180:181] op_sel_hi:[1,0]
	v_pk_mul_f32 v[34:35], v[34:35], v[180:181] op_sel_hi:[1,0]
	v_pk_mul_f32 v[32:33], v[32:33], v[180:181] op_sel_hi:[1,0]

; #define LAS __attribute__((address_space(3)))
; DI float xh_max(float x) { const unsigned u = __float_as_uint(x); const auto r = __builtin_amdgcn_permlane32_swap(u, u, false, false); return fmaxf(__uint_as_float(r[0]), __uint_as_float(r[1])); }
; DI float xh_sum(float x) { const unsigned u = __float_as_uint(x); const auto r = __builtin_amdgcn_permlane32_swap(u, u, false, false); return __uint_as_float(r[0]) + __uint_as_float(r[1]); }
; #define MFMA32(a, b, c) __builtin_amdgcn_mfma_f32_32x32x16_bf16((a), (b), (c), 0, 0, 0)
; DI f32x16 co_qk1(LAS unsigned char* st, const bf16x8 (&qf)[8], int ka_in) {
;     const int ka = ka_in;
;     f32x16 S;
; #pragma unroll
;     for (int i = 0; i < 16; ++i) S[i] = 0.f;
;     __builtin_amdgcn_s_setprio(1);
; #pragma unroll
;     for (int ks = 0; ks < 8; ++ks) { const bf16x8 a = *(const LAS bf16x8*)(st + (ka ^ (32 * ks))); S = MFMA32(a, qf[ks], S); }
;     __builtin_amdgcn_s_setprio(0);
;     return S;
; }
; template <int MODE>
; DI void co_finish(f32x16 S, LAS unsigned char* st, int key_base, AttnState& as, int tq, bool rowsel, int vb_in, int hh) {
;     const int vb = vb_in;
;     {
;         const int base = key_base + 4 * hh;
;         const int hi = (MODE == 0) ? (((tq - 31) >> 4) - base) : (tq - base);
;         const int lo = hi - 512;
; #pragma unroll
;         for (int i = 0; i < 16; ++i) { const int c = (i & 3) + 8 * (i >> 2); bool ok = (c <= hi); if (MODE == 2) ok = ok && (c > lo); if (MODE == 1) ok = ok && rowsel; S[i] = ok ? S[i] : -1e30f; }
;     }
;     float mx = S[0];
; #pragma unroll
;     for (int i = 1; i < 16; ++i) mx = fmaxf(mx, S[i]);
;     mx = xh_max(mx);
;     const float mxs = mx * SM_SCALE; const bool need = mxs > as.m + 8.f;
;     const float mnew = need ? mxs : as.m, muse = -fmaxf(mnew, -1e20f); float ps = 0.f;
; #pragma unroll
;     for (int i = 0; i < 16; ++i) { const float p = __builtin_amdgcn_exp2f(__builtin_fmaf(S[i], SM_SCALE, muse)); S[i] = p; ps += p; }
;     ps = xh_sum(ps);
;     if (__builtin_amdgcn_ballot_w64(need) != 0ull) {
;         const float alpha = __builtin_amdgcn_exp2f(as.m - mnew);
;         as.l *= alpha;
; #pragma unroll
;         for (int dt = 0; dt < 4; ++dt)
; #pragma unroll
;             for (int i = 0; i < 16; ++i) as.acc[dt][i] *= alpha;
;     }
.Lfs_win:
	v_add_u32_e32 v248, s16, v162
	ds_read_b128 v[240:243], v248
	v_add_u32_e32 v248, s16, v164
	ds_read_b128 v[244:247], v248
	v_add_u32_e32 v0, s79, v145
	v_cmp_gt_u32_e32 vcc, s53, v0
	v_add_u32_e32 v3, -1, v0
	v_add_u32_e32 v4, -2, v0
	v_cndmask_b32_e32 v2, v153, v16, vcc
	v_cmp_gt_u32_e32 vcc, s53, v3
	v_add_u32_e32 v5, -3, v0
	v_add_u32_e32 v6, -8, v0
	v_cndmask_b32_e32 v3, v153, v17, vcc
	v_cmp_gt_u32_e32 vcc, s53, v4
	v_add_u32_e32 v7, -9, v0
	v_add_u32_e32 v8, -10, v0
	v_cndmask_b32_e32 v4, v153, v18, vcc
	s_waitcnt lgkmcnt(1)
	v_mfma_f32_32x32x16_bf16 v[96:111], v[240:243], v[112:115], 0
	v_add_u32_e32 v248, s16, v165
	ds_read_b128 v[240:243], v248
	v_cmp_gt_u32_e32 vcc, s53, v5
	v_add_u32_e32 v9, -11, v0
	v_add_u32_e32 v10, -16, v0
	v_cndmask_b32_e32 v5, v153, v19, vcc
	v_cmp_gt_u32_e32 vcc, s53, v6
	v_subrev_u32_e32 v11, 17, v0
	v_subrev_u32_e32 v12, 18, v0
	v_cndmask_b32_e32 v6, v153, v20, vcc
	v_cmp_gt_u32_e32 vcc, s53, v7
	v_subrev_u32_e32 v13, 19, v0
	v_subrev_u32_e32 v14, 24, v0
	v_cndmask_b32_e32 v7, v153, v21, vcc
	v_cmp_gt_u32_e32 vcc, s53, v8
	s_waitcnt lgkmcnt(1)
	v_mfma_f32_32x32x16_bf16 v[96:111], v[244:247], v[116:119], v[96:111]
	v_add_u32_e32 v248, s16, v166
	ds_read_b128 v[244:247], v248
	v_subrev_u32_e32 v15, 25, v0
	v_subrev_u32_e32 v176, 26, v0
	v_cndmask_b32_e32 v8, v153, v22, vcc
	v_cmp_gt_u32_e32 vcc, s53, v9
	v_subrev_u32_e32 v0, 27, v0
	s_nop 0
	v_cndmask_b32_e32 v9, v153, v23, vcc
	v_cmp_gt_u32_e32 vcc, s53, v10
	s_nop 1
	v_cndmask_b32_e32 v10, v153, v24, vcc
	v_cmp_gt_u32_e32 vcc, s53, v11
	s_nop 1
	v_cndmask_b32_e32 v11, v153, v25, vcc
	s_waitcnt lgkmcnt(1)
	v_mfma_f32_32x32x16_bf16 v[96:111], v[240:243], v[120:123], v[96:111]
	v_add_u32_e32 v248, s16, v167
	ds_read_b128 v[240:243], v248
	v_cmp_gt_u32_e32 vcc, s53, v12
	s_nop 1
	v_cndmask_b32_e32 v12, v153, v26, vcc
	v_cmp_gt_u32_e32 vcc, s53, v13
	s_nop 1
	v_cndmask_b32_e32 v13, v153, v27, vcc
	v_cmp_gt_u32_e32 vcc, s53, v14
	s_nop 1
	v_cndmask_b32_e32 v14, v153, v28, vcc
	v_cmp_gt_u32_e32 vcc, s53, v15
	s_nop 1
	v_cndmask_b32_e32 v15, v153, v29, vcc
	v_cmp_gt_u32_e32 vcc, s53, v176
	s_waitcnt lgkmcnt(1)
	v_mfma_f32_32x32x16_bf16 v[96:111], v[244:247], v[124:127], v[96:111]
	v_add_u32_e32 v248, s16, v168
	ds_read_b128 v[244:247], v248
	v_max_f32_e32 v176, v3, v3
	s_nop 0
	v_cndmask_b32_e32 v178, v153, v30, vcc
	v_cmp_gt_u32_e32 vcc, s53, v0
	v_max_f32_e32 v0, v2, v2
	v_max_f32_e32 v0, v0, v176
	v_max3_f32 v0, v0, v4, v5
	v_max3_f32 v0, v0, v6, v7
	v_max3_f32 v0, v0, v8, v9
	v_max3_f32 v0, v0, v10, v11
	v_max3_f32 v0, v0, v12, v13
	v_cndmask_b32_e32 v179, v153, v31, vcc
	v_max3_f32 v0, v0, v14, v15
	s_waitcnt lgkmcnt(1)
	v_mfma_f32_32x32x16_bf16 v[96:111], v[240:243], v[128:131], v[96:111]
	v_add_u32_e32 v248, s16, v169
	ds_read_b128 v[240:243], v248
	v_max3_f32 v0, v0, v178, v179
	v_mov_b32_e32 v176, v0
	s_nop 1
	v_permlane32_swap_b32_e32 v0, v176
	v_max_f32_e32 v176, v176, v176
	v_max_f32_e32 v0, v0, v0
	v_max_f32_e32 v0, v0, v176
	v_mul_f32_e32 v0, 0x3e0293ee, v0
	v_add_f32_e32 v176, 0x41000000, v177
	v_cmp_gt_f32_e32 vcc, v0, v176
	s_nop 1
	v_cndmask_b32_e32 v176, v177, v0, vcc
	v_max_f32_e32 v0, v176, v176
	s_waitcnt lgkmcnt(1)
	v_mfma_f32_32x32x16_bf16 v[96:111], v[244:247], v[132:135], v[96:111]
	v_add_u32_e32 v248, s16, v170
	ds_read_b128 v[244:247], v248
	v_max_f32_e32 v180, 0xe0ad78ec, v0
	v_fma_f32 v0, v2, s52, -v180
	v_exp_f32_e32 v0, v0
	v_fma_f32 v2, v3, s52, -v180
	v_exp_f32_e32 v2, v2
	v_fma_f32 v3, v4, s52, -v180
	v_exp_f32_e32 v3, v3
	v_fma_f32 v4, v5, s52, -v180
	v_exp_f32_e32 v4, v4
	v_add_f32_e32 v5, 0, v0
	v_add_f32_e32 v5, v2, v5
	v_add_f32_e32 v5, v3, v5
	v_add_f32_e32 v181, v4, v5
	s_waitcnt lgkmcnt(1)
	v_mfma_f32_32x32x16_bf16 v[96:111], v[240:243], v[136:139], v[96:111]
	v_fma_f32 v5, v6, s52, -v180
	v_exp_f32_e32 v5, v5
	v_fma_f32 v6, v7, s52, -v180
	v_exp_f32_e32 v6, v6
	v_fma_f32 v7, v8, s52, -v180
	v_exp_f32_e32 v7, v7
	v_fma_f32 v8, v9, s52, -v180
	v_exp_f32_e32 v8, v8
	v_add_f32_e32 v9, v5, v181
	v_add_f32_e32 v9, v6, v9
	v_add_f32_e32 v9, v7, v9
	v_add_f32_e32 v181, v8, v9
	v_fma_f32 v9, v10, s52, -v180
	s_waitcnt lgkmcnt(0)
	v_mfma_f32_32x32x16_bf16 v[96:111], v[244:247], v[140:143], v[96:111]
	v_exp_f32_e32 v9, v9
	v_fma_f32 v10, v11, s52, -v180
	v_exp_f32_e32 v10, v10
	v_fma_f32 v11, v12, s52, -v180
	v_exp_f32_e32 v11, v11
	v_fma_f32 v12, v13, s52, -v180
	v_exp_f32_e32 v12, v12
	v_add_f32_e32 v13, v9, v181
	v_add_f32_e32 v13, v10, v13
	v_add_f32_e32 v13, v11, v13
	v_add_f32_e32 v181, v12, v13
	v_fma_f32 v13, v14, s52, -v180
	v_exp_f32_e32 v13, v13
	v_fma_f32 v14, v15, s52, -v180
	v_exp_f32_e32 v14, v14
	v_fma_f32 v15, v178, s52, -v180
	v_exp_f32_e32 v15, v15
	v_fma_f32 v178, v179, s52, -v180
	v_exp_f32_e32 v178, v178
	v_add_f32_e32 v179, v13, v181
	v_add_f32_e32 v179, v14, v179
	v_add_f32_e32 v179, v15, v179
	v_add_f32_e32 v179, v178, v179
	v_mov_b32_e32 v180, v179
	s_nop 1
	v_permlane32_swap_b32_e32 v179, v180
	s_cbranch_vccz .Lfs_win_520
	v_sub_f32_e32 v177, v177, v176
	v_exp_f32_e32 v182, v177
	s_nop 0
	v_mul_f32_e32 v175, v175, v182
	v_pk_mul_f32 v[94:95], v[94:95], v[182:183] op_sel_hi:[1,0]
	v_pk_mul_f32 v[92:93], v[92:93], v[182:183] op_sel_hi:[1,0]
	v_pk_mul_f32 v[90:91], v[90:91], v[182:183] op_sel_hi:[1,0]
	v_pk_mul_f32 v[88:89], v[88:89], v[182:183] op_sel_hi:[1,0]
	v_pk_mul_f32 v[86:87], v[86:87], v[182:183] op_sel_hi:[1,0]
	v_pk_mul_f32 v[84:85], v[84:85], v[182:183] op_sel_hi:[1,0]
	v_pk_mul_f32 v[82:83], v[82:83], v[182:183] op_sel_hi:[1,0]
	v_pk_mul_f32 v[80:81], v[80:81], v[182:183] op_sel_hi:[1,0]
	v_pk_mul_f32 v[78:79], v[78:79], v[182:183] op_sel_hi:[1,0]
	v_pk_mul_f32 v[76:77], v[76:77], v[182:183] op_sel_hi:[1,0]
	v_pk_mul_f32 v[74:75], v[74:75], v[182:183] op_sel_hi:[1,0]
	v_pk_mul_f32 v[72:73], v[72:73], v[182:183] op_sel_hi:[1,0]
	v_pk_mul_f32 v[70:71], v[70:71], v[182:183] op_sel_hi:[1,0]
	v_pk_mul_f32 v[68:69], v[68:69], v[182:183] op_sel_hi:[1,0]
	v_pk_mul_f32 v[66:67], v[66:67], v[182:183] op_sel_hi:[1,0]
	v_pk_mul_f32 v[64:65], v[64:65], v[182:183] op_sel_hi:[1,0]
	v_pk_mul_f32 v[62:63], v[62:63], v[182:183] op_sel_hi:[1,0]
	v_pk_mul_f32 v[60:61], v[60:61], v[182:183] op_sel_hi:[1,0]
	v_pk_mul_f32 v[58:59], v[58:59], v[182:183] op_sel_hi:[1,0]
	v_pk_mul_f32 v[56:57], v[56:57], v[182:183] op_sel_hi:[1,0]
	v_pk_mul_f32 v[54:55], v[54:55], v[182:183] op_sel_hi:[1,0]
	v_pk_mul_f32 v[52:53], v[52:53], v[182:183] op_sel_hi:[1,0]
	v_pk_mul_f32 v[50:51], v[50:51], v[182:183] op_sel_hi:[1,0]
	v_pk_mul_f32 v[48:49], v[48:49], v[182:183] op_sel_hi:[1,0]
	v_pk_mul_f32 v[46:47], v[46:47], v[182:183] op_sel_hi:[1,0]
	v_pk_mul_f32 v[44:45], v[44:45], v[182:183] op_sel_hi:[1,0]
	v_pk_mul_f32 v[42:43], v[42:43], v[182:183] op_sel_hi:[1,0]
	v_pk_mul_f32 v[40:41], v[40:41], v[182:183] op_sel_hi:[1,0]
	v_pk_mul_f32 v[38:39], v[38:39], v[182:183] op_sel_hi:[1,0]
	v_pk_mul_f32 v[36:37], v[36:37], v[182:183] op_sel_hi:[1,0]
	v_pk_mul_f32 v[34:35], v[34:35], v[182:183] op_sel_hi:[1,0]
	v_pk_mul_f32 v[32:33], v[32:33], v[182:183] op_sel_hi:[1,0]
